# bundle of small de-serialisations: exchange partial loads, EpiOutMod vector loads before the spin, EpiOutFin groups 2/7, D bias staging unroll, no s_sleep in flag polls
# baseline (speedup 1.0000x reference)
;     __device__ __forceinline__ void fused(f32x4 (&acc)[2][2][4][2], const Unit& u, int wr, int wc, int fr, int fq, PG8_LAS unsigned char* lds, int wid, int lane) const {
;     ...
;         if (t == 0) {
;             __hip_atomic_fetch_add(cnt + 64 * u.pm, 1u, __ATOMIC_RELAXED, __HIP_MEMORY_SCOPE_AGENT);
;             unsigned sp = 0;
;             while (__hip_atomic_load(cnt + 64 * u.pm, __ATOMIC_RELAXED, __HIP_MEMORY_SCOPE_AGENT) < 4u) { __builtin_amdgcn_s_sleep(1); if (++sp > (1u << 22)) break; }
;         }
.Lfs6_poll:
	global_load_dword v4, v5, s[98:99] sc1
	s_add_i32 m0, m0, 1
	s_waitcnt vmcnt(0)
	v_cmp_ge_u32_e32 vcc, v4, v6
	s_cmp_eq_u64 vcc, exec
	s_cbranch_scc1 .Lfs6_done
	s_cmp_lt_u32 m0, 0x20000
	s_cbranch_scc1 .Lfs6_poll
